# norm_res: both rows' loads (32) issued before the first wait; row-0 bf16 residual unpacked in place with counted vmcnt(23..16)
# baseline (speedup 1.0000x reference)
; DI float bflo(unsigned w) { return __uint_as_float(w << 16); }
; DI float bfhi(unsigned w) { return __uint_as_float(w & 0xffff0000u); }
; DI const float* xin_row(const Params& P, int t) { return t < 8192 ? P.in(0) + (size_t)t * DM : P.in(1) + (size_t)(t - 8192) * DM; }
; DI void norm_res(const Params& P, bool src_in, bool dst_out, const bf16_t* tmp, const float* gpost, const float* gpre, bf16_t* h) {
;     ...
;     for (int t0 = blockIdx.x * 8 + wid; t0 < T; t0 += 2 * stride) {
;         u32x2 wt[2][8]; f32x4 xv[2][8];
; #pragma unroll
;         for (int r = 0; r < 2; ++r) { const int t = t0 + r * stride;
; #pragma unroll
;             for (int j = 0; j < 8; ++j) wt[r][j] = *(const u32x2*)(tmp + (size_t)t * DM + j * 256 + lane * 4);
;             if (src_in) { const float* xs = xin_row(P, t);
; #pragma unroll
;                 for (int j = 0; j < 8; ++j) xv[r][j] = *(const f32x4*)(xs + j * 256 + lane * 4);
;             } else {
; #pragma unroll
;                 for (int j = 0; j < 8; ++j) { const u32x2 w = *(const u32x2*)(x16 + (size_t)t * DM + j * 256 + lane * 4); xv[r][j] = (f32x4){bflo(w.x), bfhi(w.x), bflo(w.y), bfhi(w.y)}; } } }
.LBB0_420:
	v_ashrrev_i32_e32 v161, 31, v160
	v_lshlrev_b64 v[158:159], 12, v[160:161]
	v_lshl_add_u64 v[66:67], v[146:147], 0, v[158:159]
	global_load_dwordx2 v[144:145], v[66:67], off
	global_load_dwordx2 v[142:143], v[66:67], off offset:512
	global_load_dwordx2 v[140:141], v[66:67], off offset:1024
	global_load_dwordx2 v[138:139], v[66:67], off offset:1536
	global_load_dwordx2 v[136:137], v[66:67], off offset:2048
	global_load_dwordx2 v[134:135], v[66:67], off offset:2560
	global_load_dwordx2 v[132:133], v[66:67], off offset:3072
	global_load_dwordx2 v[130:131], v[66:67], off offset:3584
	v_cndmask_b32_e64 v66, 0, 1, s[64:65]
	s_mov_b64 s[70:71], -1
	v_cmp_ne_u32_e64 s[6:7], 1, v66
	s_andn2_b64 vcc, exec, s[64:65]
	v_lshl_add_u64 v[178:179], v[148:149], 0, v[158:159]
	s_cbranch_vccnz .LBB0_422
	global_load_dwordx2 v[100:101], v[178:179], off
	global_load_dwordx2 v[104:105], v[178:179], off offset:512
	global_load_dwordx2 v[108:109], v[178:179], off offset:1024
	global_load_dwordx2 v[112:113], v[178:179], off offset:1536
	global_load_dwordx2 v[116:117], v[178:179], off offset:2048
	global_load_dwordx2 v[120:121], v[178:179], off offset:2560
	global_load_dwordx2 v[124:125], v[178:179], off offset:3072
	global_load_dwordx2 v[128:129], v[178:179], off offset:3584
	s_mov_b64 s[70:71], 0

; DI float bflo(unsigned w) { return __uint_as_float(w << 16); }
; DI float bfhi(unsigned w) { return __uint_as_float(w & 0xffff0000u); }
; DI const float* xin_row(const Params& P, int t) { return t < 8192 ? P.in(0) + (size_t)t * DM : P.in(1) + (size_t)(t - 8192) * DM; }
; DI void norm_res(const Params& P, bool src_in, bool dst_out, const bf16_t* tmp, const float* gpost, const float* gpre, bf16_t* h) {
;     ...
;         for (int r = 0; r < 2; ++r) { const int t = t0 + r * stride;
; #pragma unroll
;             for (int j = 0; j < 8; ++j) wt[r][j] = *(const u32x2*)(tmp + (size_t)t * DM + j * 256 + lane * 4);
;             if (src_in) { const float* xs = xin_row(P, t);
; #pragma unroll
;                 for (int j = 0; j < 8; ++j) xv[r][j] = *(const f32x4*)(xs + j * 256 + lane * 4);
;             } else {
; #pragma unroll
;                 for (int j = 0; j < 8; ++j) { const u32x2 w = *(const u32x2*)(x16 + (size_t)t * DM + j * 256 + lane * 4); xv[r][j] = (f32x4){bflo(w.x), bfhi(w.x), bflo(w.y), bfhi(w.y)}; } } }
.LBB0_428:
	v_add_u32_e32 v152, s87, v160
	v_ashrrev_i32_e32 v153, 31, v152
	v_lshlrev_b64 v[154:155], 12, v[152:153]
	v_lshl_add_u64 v[66:67], v[146:147], 0, v[154:155]
	global_load_dwordx2 v[176:177], v[66:67], off
	global_load_dwordx2 v[174:175], v[66:67], off offset:512
	global_load_dwordx2 v[172:173], v[66:67], off offset:1024
	global_load_dwordx2 v[170:171], v[66:67], off offset:1536
	global_load_dwordx2 v[168:169], v[66:67], off offset:2048
	global_load_dwordx2 v[166:167], v[66:67], off offset:2560
	global_load_dwordx2 v[164:165], v[66:67], off offset:3072
	global_load_dwordx2 v[162:163], v[66:67], off offset:3584
	s_mov_b64 s[70:71], -1
	s_and_b64 vcc, exec, s[6:7]
	v_lshl_add_u64 v[156:157], v[148:149], 0, v[154:155]
	s_cbranch_vccnz .LBB0_430
	global_load_dwordx2 v[68:69], v[156:157], off
	global_load_dwordx2 v[72:73], v[156:157], off offset:512
	global_load_dwordx2 v[76:77], v[156:157], off offset:1024
	global_load_dwordx2 v[80:81], v[156:157], off offset:1536
	global_load_dwordx2 v[84:85], v[156:157], off offset:2048
	global_load_dwordx2 v[88:89], v[156:157], off offset:2560
	global_load_dwordx2 v[92:93], v[156:157], off offset:3072
	global_load_dwordx2 v[96:97], v[156:157], off offset:3584
	s_mov_b64 s[70:71], 0
	s_waitcnt vmcnt(23)
	v_lshlrev_b32_e32 v98, 16, v100
	v_and_b32_e32 v99, 0xffff0000, v100
	v_lshlrev_b32_e32 v100, 16, v101
	v_and_b32_e32 v101, 0xffff0000, v101
	s_waitcnt vmcnt(22)
	v_lshlrev_b32_e32 v102, 16, v104
	v_and_b32_e32 v103, 0xffff0000, v104
	v_lshlrev_b32_e32 v104, 16, v105
	v_and_b32_e32 v105, 0xffff0000, v105
	s_waitcnt vmcnt(21)
	v_lshlrev_b32_e32 v106, 16, v108
	v_and_b32_e32 v107, 0xffff0000, v108
	v_lshlrev_b32_e32 v108, 16, v109
	v_and_b32_e32 v109, 0xffff0000, v109
	s_waitcnt vmcnt(20)
	v_lshlrev_b32_e32 v110, 16, v112
	v_and_b32_e32 v111, 0xffff0000, v112
	v_lshlrev_b32_e32 v112, 16, v113
	v_and_b32_e32 v113, 0xffff0000, v113
	s_waitcnt vmcnt(19)
	v_lshlrev_b32_e32 v114, 16, v116
	v_and_b32_e32 v115, 0xffff0000, v116
	v_lshlrev_b32_e32 v116, 16, v117
	v_and_b32_e32 v117, 0xffff0000, v117
	s_waitcnt vmcnt(18)
	v_lshlrev_b32_e32 v118, 16, v120
	v_and_b32_e32 v119, 0xffff0000, v120
	v_lshlrev_b32_e32 v120, 16, v121
	v_and_b32_e32 v121, 0xffff0000, v121
	s_waitcnt vmcnt(17)
	v_lshlrev_b32_e32 v122, 16, v124
	v_and_b32_e32 v123, 0xffff0000, v124
	v_lshlrev_b32_e32 v124, 16, v125
	v_and_b32_e32 v125, 0xffff0000, v125
	s_waitcnt vmcnt(16)
	v_lshlrev_b32_e32 v126, 16, v128
	v_and_b32_e32 v127, 0xffff0000, v128
	v_lshlrev_b32_e32 v128, 16, v129
	v_and_b32_e32 v129, 0xffff0000, v129
	s_waitcnt vmcnt(7)
	v_lshlrev_b32_e32 v66, 16, v68
	v_and_b32_e32 v67, 0xffff0000, v68
	v_lshlrev_b32_e32 v68, 16, v69
	v_and_b32_e32 v69, 0xffff0000, v69
	s_waitcnt vmcnt(6)
	v_lshlrev_b32_e32 v70, 16, v72
	v_and_b32_e32 v71, 0xffff0000, v72
	v_lshlrev_b32_e32 v72, 16, v73
	v_and_b32_e32 v73, 0xffff0000, v73
	s_waitcnt vmcnt(5)
	v_lshlrev_b32_e32 v74, 16, v76
	v_and_b32_e32 v75, 0xffff0000, v76
	v_lshlrev_b32_e32 v76, 16, v77
	v_and_b32_e32 v77, 0xffff0000, v77
	s_waitcnt vmcnt(4)
	v_lshlrev_b32_e32 v78, 16, v80
	v_and_b32_e32 v79, 0xffff0000, v80
	v_lshlrev_b32_e32 v80, 16, v81
	v_and_b32_e32 v81, 0xffff0000, v81
	s_waitcnt vmcnt(3)
	v_lshlrev_b32_e32 v82, 16, v84
	v_and_b32_e32 v83, 0xffff0000, v84
	v_lshlrev_b32_e32 v84, 16, v85
	v_and_b32_e32 v85, 0xffff0000, v85
	s_waitcnt vmcnt(2)
	v_lshlrev_b32_e32 v86, 16, v88
	v_and_b32_e32 v87, 0xffff0000, v88
	v_lshlrev_b32_e32 v88, 16, v89
	v_and_b32_e32 v89, 0xffff0000, v89
	s_waitcnt vmcnt(1)
	v_lshlrev_b32_e32 v90, 16, v92
	v_and_b32_e32 v91, 0xffff0000, v92
	v_lshlrev_b32_e32 v92, 16, v93
	v_and_b32_e32 v93, 0xffff0000, v93
	s_waitcnt vmcnt(0)
	v_lshlrev_b32_e32 v94, 16, v96
	v_and_b32_e32 v95, 0xffff0000, v96
	v_lshlrev_b32_e32 v96, 16, v97
	v_and_b32_e32 v97, 0xffff0000, v97
